# sample RWKV scan stages its k-vectors once per wave in LDS via LDS-DMA and reads them back broadcast (fewer VMEM return bytes); f32 math unchanged
# speedup vs baseline: 1.0674x; 1.0227x over previous
.LBB0_636:
	s_andn2_saveexec_b64 s[10:11], s[16:17]
	s_cbranch_execz .LBB0_676
	s_setprio 3
	v_readlane_b32 s2, v240, 10
	v_readfirstlane_b32 s3, v0
	v_and_b32_e32 v118, 63, v190
	v_and_b32_e32 v119, 15, v118
	v_lshrrev_b32_e32 v120, 4, v118
	v_and_b32_e32 v121, 1, v119
	v_cmp_ne_u32_e64 s[100:101], 0, v121
	s_mul_i32 s19, s3, 0x5000
	s_add_u32 s19, s19, 0x18600
	v_lshl_add_u32 v112, v119, 4, s19
	s_lshl_b32 s2, s2, 1
	s_add_i32 s2, s2, s3
	s_add_u32 s36, s92, 0x17c24000
	s_addc_u32 s37, s93, 0
	s_and_b32 s37, s37, 0xffff
	s_mov_b32 s38, 0x20000000
	s_mov_b32 s39, 0x20000
	s_add_u32 s40, s92, 0x23c24000
	s_addc_u32 s41, s93, 0
	s_and_b32 s41, s41, 0xffff
	s_mov_b32 s42, 0x20000000
	s_mov_b32 s43, 0x20000
	s_mov_b32 s44, s90
	s_mov_b32 s45, s91
	s_and_b32 s45, s45, 0xffff
	s_mov_b32 s46, 0x10000000
	s_mov_b32 s47, 0x20000
.Lss_item:
	s_cmpk_lt_i32 s2, 0x200
	s_cbranch_scc0 .Lss_done
	s_and_b32 s3, s2, 7
	s_lshr_b32 s99, s2, 3
	s_bfe_u32 s98, s99, 0x10004
	s_lshr_b32 s25, s99, 5
	s_and_b32 s99, s99, 15
	s_lshl_b32 s24, s25, 1
	s_add_i32 s24, s24, s98
	s_lshl_b32 s24, s24, 4
	s_add_i32 s24, s24, s99
	s_lshl_b32 s24, s24, 14
	v_readlane_b32 s8, v241, 27
	v_readlane_b32 s9, v241, 28
	s_add_u32 s8, s8, s24
	s_addc_u32 s9, s9, 0
	s_lshl_b32 s24, s3, 11
	v_lshlrev_b32_e32 v118, 9, v120
	v_lshl_add_u32 v118, v119, 4, v118
	v_add_u32_e32 v118, s24, v118
	s_nop 0
	global_load_dwordx4 v[80:83], v118, s[8:9]
	global_load_dwordx4 v[84:87], v118, s[8:9] offset:256
	s_mul_i32 s25, s98, 0xffffe000
	s_addk_i32 s25, 0x1000
	s_lshl_b32 s30, s25, 1
	s_lshl_b32 s17, s25, 2
	s_lshl_b32 s18, s25, 3
	s_lshl_b32 s24, s99, 8
	v_lshl_add_u32 v123, v119, 4, s24
	s_lshl_b32 s99, s98, 12
	v_add_u32_e32 v124, s99, v123
	s_lshl_b32 s3, s3, 5
	s_add_i32 s3, s3, s24
	v_lshl_add_u32 v122, v120, 3, s3
	v_lshl_add_u32 v110, v121, 2, v122
	v_add_u32_e32 v110, s99, v110
	v_add_u32_e32 v111, 0x8000000, v122
	v_mul_lo_u32 v125, v120, s25
	v_add_u32_e32 v123, v123, v125
	v_lshl_add_u32 v124, v125, 1, v124
	v_add_u32_e32 v113, 0x4010000, v123
	v_add_u32_e32 v114, 0xfc00, v123
	v_add_u32_e32 v115, 0xf800, v124
	v_add_u32_e32 v116, 0x800f400, v124
	v_add_u32_e32 v117, 0x10010000, v124
	s_lshl_b32 s22, s25, 0
	s_bfe_u32 s22, s2, 0x10007
	s_lshr_b32 s23, s2, 8
	s_lshl_b32 s23, s23, 12
	s_addk_i32 s23, 0x2000
	s_mul_i32 s22, s22, 0xfff
	s_add_i32 s23, s23, s22
	s_lshl_b32 s8, s23, 12
	s_lshl_b32 s24, s23, 13
	s_sub_u32 s9, s8, 0x10000
	s_sub_u32 s16, s24, 0x10000
	s_mov_b64 s[20:21], 0
	s_add_u32 m0, s19, 0x0
	s_nop 0
	buffer_load_dwordx4 v113, s[36:39], s9 offen lds
	buffer_load_dwordx4 v114, s[36:39], s9 offen offset:1024 lds
	buffer_load_dwordx4 v115, s[40:43], s16 offen offset:2048 lds
	buffer_load_dwordx4 v116, s[40:43], s16 offen offset:3072 lds
	s_add_u32 m0, s19, 0x1000
	s_nop 0
	buffer_load_dwordx4 v117, s[40:43], s16 offen lds
	s_add_u32 m0, s19, 0x1400
	s_add_i32 s9, s9, s17
	s_nop 0
	buffer_load_dwordx4 v113, s[36:39], s9 offen lds
	s_add_i32 s16, s16, s18
	buffer_load_dwordx4 v114, s[36:39], s9 offen offset:1024 lds
	buffer_load_dwordx4 v115, s[40:43], s16 offen offset:2048 lds
	buffer_load_dwordx4 v116, s[40:43], s16 offen offset:3072 lds
	s_add_u32 m0, s19, 0x2400
	s_nop 0
	buffer_load_dwordx4 v117, s[40:43], s16 offen lds
	s_add_u32 m0, s19, 0x2800
	s_add_i32 s9, s9, s17
	s_nop 0
	buffer_load_dwordx4 v113, s[36:39], s9 offen lds
	s_add_i32 s16, s16, s18
	buffer_load_dwordx4 v114, s[36:39], s9 offen offset:1024 lds
	buffer_load_dwordx4 v115, s[40:43], s16 offen offset:2048 lds
	buffer_load_dwordx4 v116, s[40:43], s16 offen offset:3072 lds
	s_add_u32 m0, s19, 0x3800
	s_nop 0
	buffer_load_dwordx4 v117, s[40:43], s16 offen lds
	buffer_load_dwordx2 v[64:65], v111, s[36:39], s8 offen
	s_add_i32 s8, s8, s25
	buffer_load_dwordx2 v[66:67], v111, s[36:39], s8 offen
	s_add_i32 s8, s8, s25
	buffer_load_dwordx2 v[68:69], v111, s[36:39], s8 offen
	s_add_i32 s8, s8, s25
	buffer_load_dwordx2 v[70:71], v111, s[36:39], s8 offen
	s_add_i32 s8, s8, s25
	buffer_load_dwordx2 v[72:73], v111, s[36:39], s8 offen
	s_add_i32 s8, s8, s25
	buffer_load_dwordx2 v[74:75], v111, s[36:39], s8 offen
	s_add_i32 s8, s8, s25
	buffer_load_dwordx2 v[76:77], v111, s[36:39], s8 offen
	s_add_i32 s8, s8, s25
	buffer_load_dwordx2 v[78:79], v111, s[36:39], s8 offen
	s_waitcnt vmcnt(18)
	ds_read_b128 v[0:3], v112 offset:0
	ds_read_b128 v[4:7], v112 offset:1024
	ds_read_b128 v[8:11], v112 offset:2048
	ds_read_b128 v[12:15], v112 offset:3072
	s_add_i32 s9, s9, s17
	s_add_i32 s16, s16, s18
	s_add_i32 s8, s8, s25
	ds_read_b128 v[16:19], v112 offset:4096
	s_movk_i32 s98, 256
	s_nop 1
.Lss_loop:
	s_mov_b64 exec, s[20:21]
	buffer_store_dword v108, v110, s[44:47], s24 offen
	s_mov_b64 exec, -1
	s_and_b32 s22, s30, s20
	s_add_i32 s24, s24, s22
	s_mov_b64 s[20:21], -1
	ds_read_b128 v[20:23], v112 offset:256
	ds_read_b128 v[24:27], v112 offset:1280
	ds_read_b128 v[28:31], v112 offset:2304
	ds_read_b128 v[32:35], v112 offset:3328
	ds_read_b128 v[36:39], v112 offset:4352
	s_waitcnt lgkmcnt(5)
	v_pk_mul_f32 v[88:89], v[80:81], v[0:1]
	v_pk_mul_f32 v[90:91], v[84:85], v[0:1]
	v_pk_fma_f32 v[88:89], v[82:83], v[2:3], v[88:89]
	v_pk_fma_f32 v[90:91], v[86:87], v[2:3], v[90:91]
	s_add_u32 m0, s19, 0x3c00
	s_nop 0
	v_add_f32_e32 v92, v88, v89
	v_add_f32_e32 v93, v90, v91
	buffer_load_dwordx4 v113, s[36:39], s9 offen lds
	buffer_load_dwordx4 v114, s[36:39], s9 offen offset:1024 lds
	buffer_load_dwordx4 v115, s[40:43], s16 offen offset:2048 lds
	v_add_f32_dpp v92, v92, v92 quad_perm:[1,0,3,2] row_mask:0xf bank_mask:0xf bound_ctrl:1
	v_add_f32_dpp v93, v93, v93 quad_perm:[1,0,3,2] row_mask:0xf bank_mask:0xf bound_ctrl:1
	buffer_load_dwordx4 v116, s[40:43], s16 offen offset:3072 lds
	s_add_u32 m0, s19, 0x4c00
	s_nop 0
	v_add_f32_dpp v92, v92, v92 quad_perm:[2,3,0,1] row_mask:0xf bank_mask:0xf bound_ctrl:1
	v_add_f32_dpp v93, v93, v93 quad_perm:[2,3,0,1] row_mask:0xf bank_mask:0xf bound_ctrl:1
	buffer_load_dwordx4 v117, s[40:43], s16 offen lds
	s_waitcnt vmcnt(13)
	v_add_f32_dpp v92, v92, v92 row_ror:4 row_mask:0xf bank_mask:0xf bound_ctrl:1
	v_add_f32_dpp v93, v93, v93 row_ror:4 row_mask:0xf bank_mask:0xf bound_ctrl:1
	v_pk_mul_f32 v[94:95], v[64:65], v[16:17] op_sel_hi:[0,1]
	v_pk_mul_f32 v[98:99], v[64:65], v[16:17] op_sel:[1,0]
	v_pk_mul_f32 v[96:97], v[64:65], v[18:19] op_sel_hi:[0,1]
	v_pk_mul_f32 v[100:101], v[64:65], v[18:19] op_sel:[1,0]
	v_pk_fma_f32 v[94:95], v[80:81], v[8:9], v[94:95]
	v_pk_fma_f32 v[98:99], v[84:85], v[8:9], v[98:99]
	v_add_f32_dpp v92, v92, v92 row_ror:8 row_mask:0xf bank_mask:0xf bound_ctrl:1
	v_add_f32_dpp v93, v93, v93 row_ror:8 row_mask:0xf bank_mask:0xf bound_ctrl:1
	v_pk_fma_f32 v[96:97], v[82:83], v[10:11], v[96:97]
	v_pk_fma_f32 v[100:101], v[86:87], v[10:11], v[100:101]
	v_pk_fma_f32 v[80:81], v[12:13], v[92:93], v[94:95] op_sel_hi:[1,0,1] neg_lo:[0,1,0] neg_hi:[0,1,0]
	v_pk_fma_f32 v[84:85], v[12:13], v[92:93], v[98:99] op_sel:[0,1,0] neg_lo:[0,1,0] neg_hi:[0,1,0]
	v_pk_fma_f32 v[82:83], v[14:15], v[92:93], v[96:97] op_sel_hi:[1,0,1] neg_lo:[0,1,0] neg_hi:[0,1,0]
	v_pk_fma_f32 v[86:87], v[14:15], v[92:93], v[100:101] op_sel:[0,1,0] neg_lo:[0,1,0] neg_hi:[0,1,0]
	v_pk_mul_f32 v[102:103], v[80:81], v[4:5]
	v_pk_mul_f32 v[104:105], v[84:85], v[4:5]
	v_pk_fma_f32 v[102:103], v[82:83], v[6:7], v[102:103]
	v_pk_fma_f32 v[104:105], v[86:87], v[6:7], v[104:105]
	ds_read_b128 v[0:3], v112 offset:512
	ds_read_b128 v[4:7], v112 offset:1536
	ds_read_b128 v[8:11], v112 offset:2560
	ds_read_b128 v[12:15], v112 offset:3584
	ds_read_b128 v[16:19], v112 offset:4608
	s_waitcnt lgkmcnt(5)
	v_pk_mul_f32 v[88:89], v[80:81], v[20:21]
	v_pk_mul_f32 v[90:91], v[84:85], v[20:21]
	v_pk_fma_f32 v[88:89], v[82:83], v[22:23], v[88:89]
	v_pk_fma_f32 v[90:91], v[86:87], v[22:23], v[90:91]
	v_add_f32_e32 v92, v88, v89
	v_add_f32_e32 v93, v90, v91
	v_add_f32_e32 v106, v102, v103
	v_add_f32_dpp v92, v92, v92 quad_perm:[1,0,3,2] row_mask:0xf bank_mask:0xf bound_ctrl:1
	v_add_f32_dpp v93, v93, v93 quad_perm:[1,0,3,2] row_mask:0xf bank_mask:0xf bound_ctrl:1
	v_add_f32_e32 v107, v104, v105
	v_add_f32_dpp v92, v92, v92 quad_perm:[2,3,0,1] row_mask:0xf bank_mask:0xf bound_ctrl:1
	v_add_f32_dpp v93, v93, v93 quad_perm:[2,3,0,1] row_mask:0xf bank_mask:0xf bound_ctrl:1
	buffer_load_dwordx2 v[64:65], v111, s[36:39], s8 offen
	s_waitcnt vmcnt(13)
	v_add_f32_dpp v92, v92, v92 row_ror:4 row_mask:0xf bank_mask:0xf bound_ctrl:1
	v_add_f32_dpp v93, v93, v93 row_ror:4 row_mask:0xf bank_mask:0xf bound_ctrl:1
	v_pk_mul_f32 v[94:95], v[66:67], v[36:37] op_sel_hi:[0,1]
	v_pk_mul_f32 v[98:99], v[66:67], v[36:37] op_sel:[1,0]
	v_pk_mul_f32 v[96:97], v[66:67], v[38:39] op_sel_hi:[0,1]
	v_pk_mul_f32 v[100:101], v[66:67], v[38:39] op_sel:[1,0]
	v_pk_fma_f32 v[94:95], v[80:81], v[28:29], v[94:95]
	v_pk_fma_f32 v[98:99], v[84:85], v[28:29], v[98:99]
	v_cndmask_b32_e64 v108, v106, v107, s[100:101]
	v_cndmask_b32_e64 v109, v107, v106, s[100:101]
	v_add_f32_dpp v92, v92, v92 row_ror:8 row_mask:0xf bank_mask:0xf bound_ctrl:1
	v_add_f32_dpp v93, v93, v93 row_ror:8 row_mask:0xf bank_mask:0xf bound_ctrl:1
	v_pk_fma_f32 v[96:97], v[82:83], v[30:31], v[96:97]
	v_pk_fma_f32 v[100:101], v[86:87], v[30:31], v[100:101]
	v_pk_fma_f32 v[80:81], v[32:33], v[92:93], v[94:95] op_sel_hi:[1,0,1] neg_lo:[0,1,0] neg_hi:[0,1,0]
	v_pk_fma_f32 v[84:85], v[32:33], v[92:93], v[98:99] op_sel:[0,1,0] neg_lo:[0,1,0] neg_hi:[0,1,0]
	v_add_f32_dpp v108, v109, v108 quad_perm:[1,0,3,2] row_mask:0xf bank_mask:0xf bound_ctrl:1
	v_pk_fma_f32 v[82:83], v[34:35], v[92:93], v[96:97] op_sel_hi:[1,0,1] neg_lo:[0,1,0] neg_hi:[0,1,0]
	v_pk_fma_f32 v[86:87], v[34:35], v[92:93], v[100:101] op_sel:[0,1,0] neg_lo:[0,1,0] neg_hi:[0,1,0]
	v_pk_mul_f32 v[102:103], v[80:81], v[24:25]
	v_pk_mul_f32 v[104:105], v[84:85], v[24:25]
	v_pk_fma_f32 v[102:103], v[82:83], v[26:27], v[102:103]
	v_pk_fma_f32 v[104:105], v[86:87], v[26:27], v[104:105]
	v_add_f32_dpp v108, v108, v108 quad_perm:[2,3,0,1] row_mask:0xf bank_mask:0xf bound_ctrl:1
	ds_read_b128 v[20:23], v112 offset:768
	ds_read_b128 v[24:27], v112 offset:1792
	v_add_f32_dpp v108, v108, v108 row_ror:4 row_mask:0xf bank_mask:0xf bound_ctrl:1
	ds_read_b128 v[28:31], v112 offset:2816
	ds_read_b128 v[32:35], v112 offset:3840
	ds_read_b128 v[36:39], v112 offset:4864
	v_add_f32_dpp v108, v108, v108 row_ror:8 row_mask:0xf bank_mask:0xf bound_ctrl:1
	s_waitcnt lgkmcnt(5)
	v_pk_mul_f32 v[88:89], v[80:81], v[0:1]
	v_pk_mul_f32 v[90:91], v[84:85], v[0:1]
	buffer_store_dword v108, v110, s[44:47], s24 offen
	v_add_f32_e32 v106, v102, v103
	v_add_f32_e32 v107, v104, v105
	v_pk_fma_f32 v[88:89], v[82:83], v[2:3], v[88:89]
	v_pk_fma_f32 v[90:91], v[86:87], v[2:3], v[90:91]
	v_cndmask_b32_e64 v108, v106, v107, s[100:101]
	v_cndmask_b32_e64 v109, v107, v106, s[100:101]
	v_add_f32_e32 v92, v88, v89
	v_add_f32_e32 v93, v90, v91
	v_add_f32_dpp v108, v109, v108 quad_perm:[1,0,3,2] row_mask:0xf bank_mask:0xf bound_ctrl:1
	v_add_f32_dpp v92, v92, v92 quad_perm:[1,0,3,2] row_mask:0xf bank_mask:0xf bound_ctrl:1
	v_add_f32_dpp v93, v93, v93 quad_perm:[1,0,3,2] row_mask:0xf bank_mask:0xf bound_ctrl:1
	v_add_f32_dpp v108, v108, v108 quad_perm:[2,3,0,1] row_mask:0xf bank_mask:0xf bound_ctrl:1
	v_add_f32_dpp v92, v92, v92 quad_perm:[2,3,0,1] row_mask:0xf bank_mask:0xf bound_ctrl:1
	v_add_f32_dpp v93, v93, v93 quad_perm:[2,3,0,1] row_mask:0xf bank_mask:0xf bound_ctrl:1
	s_add_i32 s8, s8, s25
	v_add_f32_dpp v108, v108, v108 row_ror:4 row_mask:0xf bank_mask:0xf bound_ctrl:1
	v_add_f32_dpp v92, v92, v92 row_ror:4 row_mask:0xf bank_mask:0xf bound_ctrl:1
	v_add_f32_dpp v93, v93, v93 row_ror:4 row_mask:0xf bank_mask:0xf bound_ctrl:1
	s_add_i32 s24, s24, s30
	v_add_f32_dpp v108, v108, v108 row_ror:8 row_mask:0xf bank_mask:0xf bound_ctrl:1
	buffer_load_dwordx2 v[66:67], v111, s[36:39], s8 offen
	s_waitcnt vmcnt(14)
	v_pk_mul_f32 v[94:95], v[68:69], v[16:17] op_sel_hi:[0,1]
	v_pk_mul_f32 v[98:99], v[68:69], v[16:17] op_sel:[1,0]
	v_pk_mul_f32 v[96:97], v[68:69], v[18:19] op_sel_hi:[0,1]
	v_pk_mul_f32 v[100:101], v[68:69], v[18:19] op_sel:[1,0]
	v_pk_fma_f32 v[94:95], v[80:81], v[8:9], v[94:95]
	v_pk_fma_f32 v[98:99], v[84:85], v[8:9], v[98:99]
	v_add_f32_dpp v92, v92, v92 row_ror:8 row_mask:0xf bank_mask:0xf bound_ctrl:1
	v_add_f32_dpp v93, v93, v93 row_ror:8 row_mask:0xf bank_mask:0xf bound_ctrl:1
	v_pk_fma_f32 v[96:97], v[82:83], v[10:11], v[96:97]
	v_pk_fma_f32 v[100:101], v[86:87], v[10:11], v[100:101]
	v_pk_fma_f32 v[80:81], v[12:13], v[92:93], v[94:95] op_sel_hi:[1,0,1] neg_lo:[0,1,0] neg_hi:[0,1,0]
	v_pk_fma_f32 v[84:85], v[12:13], v[92:93], v[98:99] op_sel:[0,1,0] neg_lo:[0,1,0] neg_hi:[0,1,0]
	buffer_store_dword v108, v110, s[44:47], s24 offen
	v_pk_fma_f32 v[82:83], v[14:15], v[92:93], v[96:97] op_sel_hi:[1,0,1] neg_lo:[0,1,0] neg_hi:[0,1,0]
	v_pk_fma_f32 v[86:87], v[14:15], v[92:93], v[100:101] op_sel:[0,1,0] neg_lo:[0,1,0] neg_hi:[0,1,0]
	v_pk_mul_f32 v[102:103], v[80:81], v[4:5]
	v_pk_mul_f32 v[104:105], v[84:85], v[4:5]
	v_pk_fma_f32 v[102:103], v[82:83], v[6:7], v[102:103]
	v_pk_fma_f32 v[104:105], v[86:87], v[6:7], v[104:105]
	s_add_i32 s8, s8, s25
	buffer_load_dwordx2 v[68:69], v111, s[36:39], s8 offen
	s_waitcnt vmcnt(24)
	ds_read_b128 v[0:3], v112 offset:5120
	ds_read_b128 v[4:7], v112 offset:6144
	ds_read_b128 v[8:11], v112 offset:7168
	ds_read_b128 v[12:15], v112 offset:8192
	ds_read_b128 v[16:19], v112 offset:9216
	s_waitcnt lgkmcnt(5)
	v_pk_mul_f32 v[88:89], v[80:81], v[20:21]
	v_pk_mul_f32 v[90:91], v[84:85], v[20:21]
	v_pk_fma_f32 v[88:89], v[82:83], v[22:23], v[88:89]
	v_pk_fma_f32 v[90:91], v[86:87], v[22:23], v[90:91]
	v_add_f32_e32 v92, v88, v89
	v_add_f32_e32 v93, v90, v91
	s_waitcnt vmcnt(15)
	v_add_f32_dpp v92, v92, v92 quad_perm:[1,0,3,2] row_mask:0xf bank_mask:0xf bound_ctrl:1
	v_add_f32_dpp v93, v93, v93 quad_perm:[1,0,3,2] row_mask:0xf bank_mask:0xf bound_ctrl:1
	v_pk_mul_f32 v[94:95], v[70:71], v[36:37] op_sel_hi:[0,1]
	v_add_f32_dpp v92, v92, v92 quad_perm:[2,3,0,1] row_mask:0xf bank_mask:0xf bound_ctrl:1
	v_add_f32_dpp v93, v93, v93 quad_perm:[2,3,0,1] row_mask:0xf bank_mask:0xf bound_ctrl:1
	v_pk_mul_f32 v[98:99], v[70:71], v[36:37] op_sel:[1,0]
	v_add_f32_dpp v92, v92, v92 row_ror:4 row_mask:0xf bank_mask:0xf bound_ctrl:1
	v_add_f32_dpp v93, v93, v93 row_ror:4 row_mask:0xf bank_mask:0xf bound_ctrl:1
	v_add_f32_e32 v106, v102, v103
	v_add_f32_e32 v107, v104, v105
	v_cndmask_b32_e64 v108, v106, v107, s[100:101]
	v_cndmask_b32_e64 v109, v107, v106, s[100:101]
	v_pk_mul_f32 v[96:97], v[70:71], v[38:39] op_sel_hi:[0,1]
	v_pk_mul_f32 v[100:101], v[70:71], v[38:39] op_sel:[1,0]
	v_pk_fma_f32 v[94:95], v[80:81], v[28:29], v[94:95]
	v_pk_fma_f32 v[98:99], v[84:85], v[28:29], v[98:99]
	v_add_f32_dpp v92, v92, v92 row_ror:8 row_mask:0xf bank_mask:0xf bound_ctrl:1
	v_add_f32_dpp v93, v93, v93 row_ror:8 row_mask:0xf bank_mask:0xf bound_ctrl:1
	v_pk_fma_f32 v[96:97], v[82:83], v[30:31], v[96:97]
	v_pk_fma_f32 v[100:101], v[86:87], v[30:31], v[100:101]
	v_pk_fma_f32 v[80:81], v[32:33], v[92:93], v[94:95] op_sel_hi:[1,0,1] neg_lo:[0,1,0] neg_hi:[0,1,0]
	v_pk_fma_f32 v[84:85], v[32:33], v[92:93], v[98:99] op_sel:[0,1,0] neg_lo:[0,1,0] neg_hi:[0,1,0]
	v_add_f32_dpp v108, v109, v108 quad_perm:[1,0,3,2] row_mask:0xf bank_mask:0xf bound_ctrl:1
	v_pk_fma_f32 v[82:83], v[34:35], v[92:93], v[96:97] op_sel_hi:[1,0,1] neg_lo:[0,1,0] neg_hi:[0,1,0]
	v_pk_fma_f32 v[86:87], v[34:35], v[92:93], v[100:101] op_sel:[0,1,0] neg_lo:[0,1,0] neg_hi:[0,1,0]
	v_pk_mul_f32 v[102:103], v[80:81], v[24:25]
	v_pk_mul_f32 v[104:105], v[84:85], v[24:25]
	v_add_f32_dpp v108, v108, v108 quad_perm:[2,3,0,1] row_mask:0xf bank_mask:0xf bound_ctrl:1
	v_pk_fma_f32 v[102:103], v[82:83], v[26:27], v[102:103]
	v_pk_fma_f32 v[104:105], v[86:87], v[26:27], v[104:105]
	ds_read_b128 v[20:23], v112 offset:5376
	v_add_f32_dpp v108, v108, v108 row_ror:4 row_mask:0xf bank_mask:0xf bound_ctrl:1
	ds_read_b128 v[24:27], v112 offset:6400
	s_add_i32 s9, s9, s17
	ds_read_b128 v[28:31], v112 offset:7424
	ds_read_b128 v[32:35], v112 offset:8448
	s_add_i32 s16, s16, s18
	s_add_i32 s24, s24, s30
	v_add_f32_dpp v108, v108, v108 row_ror:8 row_mask:0xf bank_mask:0xf bound_ctrl:1
	ds_read_b128 v[36:39], v112 offset:9472
	s_waitcnt lgkmcnt(5)
	v_pk_mul_f32 v[88:89], v[80:81], v[0:1]
	v_pk_mul_f32 v[90:91], v[84:85], v[0:1]
	buffer_store_dword v108, v110, s[44:47], s24 offen
	v_pk_fma_f32 v[88:89], v[82:83], v[2:3], v[88:89]
	v_pk_fma_f32 v[90:91], v[86:87], v[2:3], v[90:91]
	s_add_u32 m0, s19, 0x0
	s_nop 0
	v_add_f32_e32 v92, v88, v89
	v_add_f32_e32 v93, v90, v91
	s_add_i32 s8, s8, s25
	v_add_f32_dpp v92, v92, v92 quad_perm:[1,0,3,2] row_mask:0xf bank_mask:0xf bound_ctrl:1
	v_add_f32_dpp v93, v93, v93 quad_perm:[1,0,3,2] row_mask:0xf bank_mask:0xf bound_ctrl:1
	buffer_load_dwordx2 v[70:71], v111, s[36:39], s8 offen
	buffer_load_dwordx4 v113, s[36:39], s9 offen lds
	buffer_load_dwordx4 v114, s[36:39], s9 offen offset:1024 lds
	buffer_load_dwordx4 v115, s[40:43], s16 offen offset:2048 lds
	buffer_load_dwordx4 v116, s[40:43], s16 offen offset:3072 lds
	s_add_u32 m0, s19, 0x1000
	s_nop 0
	v_add_f32_dpp v92, v92, v92 quad_perm:[2,3,0,1] row_mask:0xf bank_mask:0xf bound_ctrl:1
	v_add_f32_dpp v93, v93, v93 quad_perm:[2,3,0,1] row_mask:0xf bank_mask:0xf bound_ctrl:1
	buffer_load_dwordx4 v117, s[40:43], s16 offen lds
	s_waitcnt vmcnt(21)
	v_add_f32_dpp v92, v92, v92 row_ror:4 row_mask:0xf bank_mask:0xf bound_ctrl:1
	v_add_f32_dpp v93, v93, v93 row_ror:4 row_mask:0xf bank_mask:0xf bound_ctrl:1
	v_pk_mul_f32 v[94:95], v[72:73], v[16:17] op_sel_hi:[0,1]
	v_pk_mul_f32 v[98:99], v[72:73], v[16:17] op_sel:[1,0]
	v_pk_mul_f32 v[96:97], v[72:73], v[18:19] op_sel_hi:[0,1]
	v_pk_mul_f32 v[100:101], v[72:73], v[18:19] op_sel:[1,0]
	v_pk_fma_f32 v[94:95], v[80:81], v[8:9], v[94:95]
	v_pk_fma_f32 v[98:99], v[84:85], v[8:9], v[98:99]
	v_add_f32_e32 v106, v102, v103
	v_add_f32_e32 v107, v104, v105
	v_add_f32_dpp v92, v92, v92 row_ror:8 row_mask:0xf bank_mask:0xf bound_ctrl:1
	v_add_f32_dpp v93, v93, v93 row_ror:8 row_mask:0xf bank_mask:0xf bound_ctrl:1
	v_pk_fma_f32 v[96:97], v[82:83], v[10:11], v[96:97]
	v_pk_fma_f32 v[100:101], v[86:87], v[10:11], v[100:101]
	v_pk_fma_f32 v[80:81], v[12:13], v[92:93], v[94:95] op_sel_hi:[1,0,1] neg_lo:[0,1,0] neg_hi:[0,1,0]
	v_pk_fma_f32 v[84:85], v[12:13], v[92:93], v[98:99] op_sel:[0,1,0] neg_lo:[0,1,0] neg_hi:[0,1,0]
	v_pk_fma_f32 v[82:83], v[14:15], v[92:93], v[96:97] op_sel_hi:[1,0,1] neg_lo:[0,1,0] neg_hi:[0,1,0]
	v_pk_fma_f32 v[86:87], v[14:15], v[92:93], v[100:101] op_sel:[0,1,0] neg_lo:[0,1,0] neg_hi:[0,1,0]
	v_pk_mul_f32 v[102:103], v[80:81], v[4:5]
	v_pk_mul_f32 v[104:105], v[84:85], v[4:5]
	v_pk_fma_f32 v[102:103], v[82:83], v[6:7], v[102:103]
	v_pk_fma_f32 v[104:105], v[86:87], v[6:7], v[104:105]
	v_cndmask_b32_e64 v108, v106, v107, s[100:101]
	v_cndmask_b32_e64 v109, v107, v106, s[100:101]
	ds_read_b128 v[0:3], v112 offset:5632
	ds_read_b128 v[4:7], v112 offset:6656
	v_add_f32_dpp v108, v109, v108 quad_perm:[1,0,3,2] row_mask:0xf bank_mask:0xf bound_ctrl:1
	ds_read_b128 v[8:11], v112 offset:7680
	ds_read_b128 v[12:15], v112 offset:8704
	ds_read_b128 v[16:19], v112 offset:9728
	v_add_f32_dpp v108, v108, v108 quad_perm:[2,3,0,1] row_mask:0xf bank_mask:0xf bound_ctrl:1
	s_waitcnt lgkmcnt(5)
	v_pk_mul_f32 v[88:89], v[80:81], v[20:21]
	v_pk_mul_f32 v[90:91], v[84:85], v[20:21]
	v_add_f32_dpp v108, v108, v108 row_ror:4 row_mask:0xf bank_mask:0xf bound_ctrl:1
	v_pk_fma_f32 v[88:89], v[82:83], v[22:23], v[88:89]
	v_pk_fma_f32 v[90:91], v[86:87], v[22:23], v[90:91]
	v_add_f32_e32 v92, v88, v89
	v_add_f32_e32 v93, v90, v91
	s_add_i32 s24, s24, s30
	v_add_f32_dpp v108, v108, v108 row_ror:8 row_mask:0xf bank_mask:0xf bound_ctrl:1
	v_add_f32_dpp v92, v92, v92 quad_perm:[1,0,3,2] row_mask:0xf bank_mask:0xf bound_ctrl:1
	v_add_f32_dpp v93, v93, v93 quad_perm:[1,0,3,2] row_mask:0xf bank_mask:0xf bound_ctrl:1
	buffer_store_dword v108, v110, s[44:47], s24 offen
	v_add_f32_dpp v92, v92, v92 quad_perm:[2,3,0,1] row_mask:0xf bank_mask:0xf bound_ctrl:1
	v_add_f32_dpp v93, v93, v93 quad_perm:[2,3,0,1] row_mask:0xf bank_mask:0xf bound_ctrl:1
	s_add_i32 s8, s8, s25
	v_add_f32_dpp v92, v92, v92 row_ror:4 row_mask:0xf bank_mask:0xf bound_ctrl:1
	v_add_f32_dpp v93, v93, v93 row_ror:4 row_mask:0xf bank_mask:0xf bound_ctrl:1
	v_add_f32_e32 v106, v102, v103
	v_add_f32_e32 v107, v104, v105
	buffer_load_dwordx2 v[72:73], v111, s[36:39], s8 offen
	s_waitcnt vmcnt(22)
	v_pk_mul_f32 v[94:95], v[74:75], v[36:37] op_sel_hi:[0,1]
	v_pk_mul_f32 v[98:99], v[74:75], v[36:37] op_sel:[1,0]
	v_pk_mul_f32 v[96:97], v[74:75], v[38:39] op_sel_hi:[0,1]
	v_pk_mul_f32 v[100:101], v[74:75], v[38:39] op_sel:[1,0]
	v_pk_fma_f32 v[94:95], v[80:81], v[28:29], v[94:95]
	v_pk_fma_f32 v[98:99], v[84:85], v[28:29], v[98:99]
	v_cndmask_b32_e64 v108, v106, v107, s[100:101]
	v_cndmask_b32_e64 v109, v107, v106, s[100:101]
	v_add_f32_dpp v92, v92, v92 row_ror:8 row_mask:0xf bank_mask:0xf bound_ctrl:1
	v_add_f32_dpp v93, v93, v93 row_ror:8 row_mask:0xf bank_mask:0xf bound_ctrl:1
	v_pk_fma_f32 v[96:97], v[82:83], v[30:31], v[96:97]
	v_pk_fma_f32 v[100:101], v[86:87], v[30:31], v[100:101]
	v_pk_fma_f32 v[80:81], v[32:33], v[92:93], v[94:95] op_sel_hi:[1,0,1] neg_lo:[0,1,0] neg_hi:[0,1,0]
	v_pk_fma_f32 v[84:85], v[32:33], v[92:93], v[98:99] op_sel:[0,1,0] neg_lo:[0,1,0] neg_hi:[0,1,0]
	v_add_f32_dpp v108, v109, v108 quad_perm:[1,0,3,2] row_mask:0xf bank_mask:0xf bound_ctrl:1
	v_pk_fma_f32 v[82:83], v[34:35], v[92:93], v[96:97] op_sel_hi:[1,0,1] neg_lo:[0,1,0] neg_hi:[0,1,0]
	v_pk_fma_f32 v[86:87], v[34:35], v[92:93], v[100:101] op_sel:[0,1,0] neg_lo:[0,1,0] neg_hi:[0,1,0]
	v_pk_mul_f32 v[102:103], v[80:81], v[24:25]
	v_pk_mul_f32 v[104:105], v[84:85], v[24:25]
	v_pk_fma_f32 v[102:103], v[82:83], v[26:27], v[102:103]
	v_pk_fma_f32 v[104:105], v[86:87], v[26:27], v[104:105]
	v_add_f32_dpp v108, v108, v108 quad_perm:[2,3,0,1] row_mask:0xf bank_mask:0xf bound_ctrl:1
	ds_read_b128 v[20:23], v112 offset:5888
	ds_read_b128 v[24:27], v112 offset:6912
	v_add_f32_dpp v108, v108, v108 row_ror:4 row_mask:0xf bank_mask:0xf bound_ctrl:1
	ds_read_b128 v[28:31], v112 offset:7936
	ds_read_b128 v[32:35], v112 offset:8960
	ds_read_b128 v[36:39], v112 offset:9984
	s_add_i32 s24, s24, s30
	v_add_f32_dpp v108, v108, v108 row_ror:8 row_mask:0xf bank_mask:0xf bound_ctrl:1
	s_waitcnt lgkmcnt(5)
	v_pk_mul_f32 v[88:89], v[80:81], v[0:1]
	v_pk_mul_f32 v[90:91], v[84:85], v[0:1]
	buffer_store_dword v108, v110, s[44:47], s24 offen
	v_add_f32_e32 v106, v102, v103
	v_add_f32_e32 v107, v104, v105
	v_pk_fma_f32 v[88:89], v[82:83], v[2:3], v[88:89]
	v_pk_fma_f32 v[90:91], v[86:87], v[2:3], v[90:91]
	v_cndmask_b32_e64 v108, v106, v107, s[100:101]
	v_cndmask_b32_e64 v109, v107, v106, s[100:101]
	v_add_f32_e32 v92, v88, v89
	v_add_f32_e32 v93, v90, v91
	v_add_f32_dpp v108, v109, v108 quad_perm:[1,0,3,2] row_mask:0xf bank_mask:0xf bound_ctrl:1
	v_add_f32_dpp v92, v92, v92 quad_perm:[1,0,3,2] row_mask:0xf bank_mask:0xf bound_ctrl:1
	v_add_f32_dpp v93, v93, v93 quad_perm:[1,0,3,2] row_mask:0xf bank_mask:0xf bound_ctrl:1
	v_add_f32_dpp v108, v108, v108 quad_perm:[2,3,0,1] row_mask:0xf bank_mask:0xf bound_ctrl:1
	v_add_f32_dpp v92, v92, v92 quad_perm:[2,3,0,1] row_mask:0xf bank_mask:0xf bound_ctrl:1
	v_add_f32_dpp v93, v93, v93 quad_perm:[2,3,0,1] row_mask:0xf bank_mask:0xf bound_ctrl:1
	s_add_i32 s8, s8, s25
	v_add_f32_dpp v108, v108, v108 row_ror:4 row_mask:0xf bank_mask:0xf bound_ctrl:1
	v_add_f32_dpp v92, v92, v92 row_ror:4 row_mask:0xf bank_mask:0xf bound_ctrl:1
	v_add_f32_dpp v93, v93, v93 row_ror:4 row_mask:0xf bank_mask:0xf bound_ctrl:1
	s_add_i32 s24, s24, s30
	v_add_f32_dpp v108, v108, v108 row_ror:8 row_mask:0xf bank_mask:0xf bound_ctrl:1
	buffer_load_dwordx2 v[74:75], v111, s[36:39], s8 offen
	s_waitcnt vmcnt(23)
	v_pk_mul_f32 v[94:95], v[76:77], v[16:17] op_sel_hi:[0,1]
	v_pk_mul_f32 v[98:99], v[76:77], v[16:17] op_sel:[1,0]
	v_pk_mul_f32 v[96:97], v[76:77], v[18:19] op_sel_hi:[0,1]
	v_pk_mul_f32 v[100:101], v[76:77], v[18:19] op_sel:[1,0]
	v_pk_fma_f32 v[94:95], v[80:81], v[8:9], v[94:95]
	v_pk_fma_f32 v[98:99], v[84:85], v[8:9], v[98:99]
	v_add_f32_dpp v92, v92, v92 row_ror:8 row_mask:0xf bank_mask:0xf bound_ctrl:1
	v_add_f32_dpp v93, v93, v93 row_ror:8 row_mask:0xf bank_mask:0xf bound_ctrl:1
	v_pk_fma_f32 v[96:97], v[82:83], v[10:11], v[96:97]
	v_pk_fma_f32 v[100:101], v[86:87], v[10:11], v[100:101]
	v_pk_fma_f32 v[80:81], v[12:13], v[92:93], v[94:95] op_sel_hi:[1,0,1] neg_lo:[0,1,0] neg_hi:[0,1,0]
	v_pk_fma_f32 v[84:85], v[12:13], v[92:93], v[98:99] op_sel:[0,1,0] neg_lo:[0,1,0] neg_hi:[0,1,0]
	buffer_store_dword v108, v110, s[44:47], s24 offen
	v_pk_fma_f32 v[82:83], v[14:15], v[92:93], v[96:97] op_sel_hi:[1,0,1] neg_lo:[0,1,0] neg_hi:[0,1,0]
	v_pk_fma_f32 v[86:87], v[14:15], v[92:93], v[100:101] op_sel:[0,1,0] neg_lo:[0,1,0] neg_hi:[0,1,0]
	v_pk_mul_f32 v[102:103], v[80:81], v[4:5]
	v_pk_mul_f32 v[104:105], v[84:85], v[4:5]
	v_pk_fma_f32 v[102:103], v[82:83], v[6:7], v[102:103]
	v_pk_fma_f32 v[104:105], v[86:87], v[6:7], v[104:105]
	s_add_i32 s8, s8, s25
	buffer_load_dwordx2 v[76:77], v111, s[36:39], s8 offen
	s_waitcnt vmcnt(32)
	ds_read_b128 v[0:3], v112 offset:10240
	ds_read_b128 v[4:7], v112 offset:11264
	ds_read_b128 v[8:11], v112 offset:12288
	ds_read_b128 v[12:15], v112 offset:13312
	ds_read_b128 v[16:19], v112 offset:14336
	s_waitcnt lgkmcnt(5)
	v_pk_mul_f32 v[88:89], v[80:81], v[20:21]
	v_pk_mul_f32 v[90:91], v[84:85], v[20:21]
	v_pk_fma_f32 v[88:89], v[82:83], v[22:23], v[88:89]
	v_pk_fma_f32 v[90:91], v[86:87], v[22:23], v[90:91]
	v_add_f32_e32 v92, v88, v89
	v_add_f32_e32 v93, v90, v91
	s_waitcnt vmcnt(24)
	v_add_f32_dpp v92, v92, v92 quad_perm:[1,0,3,2] row_mask:0xf bank_mask:0xf bound_ctrl:1
	v_add_f32_dpp v93, v93, v93 quad_perm:[1,0,3,2] row_mask:0xf bank_mask:0xf bound_ctrl:1
	v_pk_mul_f32 v[94:95], v[78:79], v[36:37] op_sel_hi:[0,1]
	v_add_f32_dpp v92, v92, v92 quad_perm:[2,3,0,1] row_mask:0xf bank_mask:0xf bound_ctrl:1
	v_add_f32_dpp v93, v93, v93 quad_perm:[2,3,0,1] row_mask:0xf bank_mask:0xf bound_ctrl:1
	v_pk_mul_f32 v[98:99], v[78:79], v[36:37] op_sel:[1,0]
	v_add_f32_dpp v92, v92, v92 row_ror:4 row_mask:0xf bank_mask:0xf bound_ctrl:1
	v_add_f32_dpp v93, v93, v93 row_ror:4 row_mask:0xf bank_mask:0xf bound_ctrl:1
	v_add_f32_e32 v106, v102, v103
	v_add_f32_e32 v107, v104, v105
	v_cndmask_b32_e64 v108, v106, v107, s[100:101]
	v_cndmask_b32_e64 v109, v107, v106, s[100:101]
	v_pk_mul_f32 v[96:97], v[78:79], v[38:39] op_sel_hi:[0,1]
	v_pk_mul_f32 v[100:101], v[78:79], v[38:39] op_sel:[1,0]
	v_pk_fma_f32 v[94:95], v[80:81], v[28:29], v[94:95]
	v_pk_fma_f32 v[98:99], v[84:85], v[28:29], v[98:99]
	v_add_f32_dpp v92, v92, v92 row_ror:8 row_mask:0xf bank_mask:0xf bound_ctrl:1
	v_add_f32_dpp v93, v93, v93 row_ror:8 row_mask:0xf bank_mask:0xf bound_ctrl:1
	v_pk_fma_f32 v[96:97], v[82:83], v[30:31], v[96:97]
	v_pk_fma_f32 v[100:101], v[86:87], v[30:31], v[100:101]
	v_pk_fma_f32 v[80:81], v[32:33], v[92:93], v[94:95] op_sel_hi:[1,0,1] neg_lo:[0,1,0] neg_hi:[0,1,0]
	v_pk_fma_f32 v[84:85], v[32:33], v[92:93], v[98:99] op_sel:[0,1,0] neg_lo:[0,1,0] neg_hi:[0,1,0]
	v_add_f32_dpp v108, v109, v108 quad_perm:[1,0,3,2] row_mask:0xf bank_mask:0xf bound_ctrl:1
	v_pk_fma_f32 v[82:83], v[34:35], v[92:93], v[96:97] op_sel_hi:[1,0,1] neg_lo:[0,1,0] neg_hi:[0,1,0]
	v_pk_fma_f32 v[86:87], v[34:35], v[92:93], v[100:101] op_sel:[0,1,0] neg_lo:[0,1,0] neg_hi:[0,1,0]
	v_pk_mul_f32 v[102:103], v[80:81], v[24:25]
	v_pk_mul_f32 v[104:105], v[84:85], v[24:25]
	v_add_f32_dpp v108, v108, v108 quad_perm:[2,3,0,1] row_mask:0xf bank_mask:0xf bound_ctrl:1
	v_pk_fma_f32 v[102:103], v[82:83], v[26:27], v[102:103]
	v_pk_fma_f32 v[104:105], v[86:87], v[26:27], v[104:105]
	ds_read_b128 v[20:23], v112 offset:10496
	v_add_f32_dpp v108, v108, v108 row_ror:4 row_mask:0xf bank_mask:0xf bound_ctrl:1
	ds_read_b128 v[24:27], v112 offset:11520
	s_add_i32 s9, s9, s17
	ds_read_b128 v[28:31], v112 offset:12544
	ds_read_b128 v[32:35], v112 offset:13568
	s_add_i32 s16, s16, s18
	s_add_i32 s24, s24, s30
	v_add_f32_dpp v108, v108, v108 row_ror:8 row_mask:0xf bank_mask:0xf bound_ctrl:1
	ds_read_b128 v[36:39], v112 offset:14592
	s_waitcnt lgkmcnt(5)
	v_pk_mul_f32 v[88:89], v[80:81], v[0:1]
	v_pk_mul_f32 v[90:91], v[84:85], v[0:1]
	buffer_store_dword v108, v110, s[44:47], s24 offen
	v_pk_fma_f32 v[88:89], v[82:83], v[2:3], v[88:89]
	v_pk_fma_f32 v[90:91], v[86:87], v[2:3], v[90:91]
	s_add_u32 m0, s19, 0x1400
	s_nop 0
	v_add_f32_e32 v92, v88, v89
	v_add_f32_e32 v93, v90, v91
	s_add_i32 s8, s8, s25
	v_add_f32_dpp v92, v92, v92 quad_perm:[1,0,3,2] row_mask:0xf bank_mask:0xf bound_ctrl:1
	v_add_f32_dpp v93, v93, v93 quad_perm:[1,0,3,2] row_mask:0xf bank_mask:0xf bound_ctrl:1
	buffer_load_dwordx2 v[78:79], v111, s[36:39], s8 offen
	buffer_load_dwordx4 v113, s[36:39], s9 offen lds
	buffer_load_dwordx4 v114, s[36:39], s9 offen offset:1024 lds
	buffer_load_dwordx4 v115, s[40:43], s16 offen offset:2048 lds
	buffer_load_dwordx4 v116, s[40:43], s16 offen offset:3072 lds
	s_add_u32 m0, s19, 0x2400
	s_nop 0
	v_add_f32_dpp v92, v92, v92 quad_perm:[2,3,0,1] row_mask:0xf bank_mask:0xf bound_ctrl:1
	v_add_f32_dpp v93, v93, v93 quad_perm:[2,3,0,1] row_mask:0xf bank_mask:0xf bound_ctrl:1
	buffer_load_dwordx4 v117, s[40:43], s16 offen lds
	s_waitcnt vmcnt(24)
	v_add_f32_dpp v92, v92, v92 row_ror:4 row_mask:0xf bank_mask:0xf bound_ctrl:1
	v_add_f32_dpp v93, v93, v93 row_ror:4 row_mask:0xf bank_mask:0xf bound_ctrl:1
	v_pk_mul_f32 v[94:95], v[64:65], v[16:17] op_sel_hi:[0,1]
	v_pk_mul_f32 v[98:99], v[64:65], v[16:17] op_sel:[1,0]
	v_pk_mul_f32 v[96:97], v[64:65], v[18:19] op_sel_hi:[0,1]
	v_pk_mul_f32 v[100:101], v[64:65], v[18:19] op_sel:[1,0]
	v_pk_fma_f32 v[94:95], v[80:81], v[8:9], v[94:95]
	v_pk_fma_f32 v[98:99], v[84:85], v[8:9], v[98:99]
	v_add_f32_e32 v106, v102, v103
	v_add_f32_e32 v107, v104, v105
	v_add_f32_dpp v92, v92, v92 row_ror:8 row_mask:0xf bank_mask:0xf bound_ctrl:1
	v_add_f32_dpp v93, v93, v93 row_ror:8 row_mask:0xf bank_mask:0xf bound_ctrl:1
	v_pk_fma_f32 v[96:97], v[82:83], v[10:11], v[96:97]
	v_pk_fma_f32 v[100:101], v[86:87], v[10:11], v[100:101]
	v_pk_fma_f32 v[80:81], v[12:13], v[92:93], v[94:95] op_sel_hi:[1,0,1] neg_lo:[0,1,0] neg_hi:[0,1,0]
	v_pk_fma_f32 v[84:85], v[12:13], v[92:93], v[98:99] op_sel:[0,1,0] neg_lo:[0,1,0] neg_hi:[0,1,0]
	v_pk_fma_f32 v[82:83], v[14:15], v[92:93], v[96:97] op_sel_hi:[1,0,1] neg_lo:[0,1,0] neg_hi:[0,1,0]
	v_pk_fma_f32 v[86:87], v[14:15], v[92:93], v[100:101] op_sel:[0,1,0] neg_lo:[0,1,0] neg_hi:[0,1,0]
	v_pk_mul_f32 v[102:103], v[80:81], v[4:5]
	v_pk_mul_f32 v[104:105], v[84:85], v[4:5]
	v_pk_fma_f32 v[102:103], v[82:83], v[6:7], v[102:103]
	v_pk_fma_f32 v[104:105], v[86:87], v[6:7], v[104:105]
	v_cndmask_b32_e64 v108, v106, v107, s[100:101]
	v_cndmask_b32_e64 v109, v107, v106, s[100:101]
	ds_read_b128 v[0:3], v112 offset:10752
	ds_read_b128 v[4:7], v112 offset:11776
	v_add_f32_dpp v108, v109, v108 quad_perm:[1,0,3,2] row_mask:0xf bank_mask:0xf bound_ctrl:1
	ds_read_b128 v[8:11], v112 offset:12800
	ds_read_b128 v[12:15], v112 offset:13824
	ds_read_b128 v[16:19], v112 offset:14848
	v_add_f32_dpp v108, v108, v108 quad_perm:[2,3,0,1] row_mask:0xf bank_mask:0xf bound_ctrl:1
	s_waitcnt lgkmcnt(5)
	v_pk_mul_f32 v[88:89], v[80:81], v[20:21]
	v_pk_mul_f32 v[90:91], v[84:85], v[20:21]
	v_add_f32_dpp v108, v108, v108 row_ror:4 row_mask:0xf bank_mask:0xf bound_ctrl:1
	v_pk_fma_f32 v[88:89], v[82:83], v[22:23], v[88:89]
	v_pk_fma_f32 v[90:91], v[86:87], v[22:23], v[90:91]
	v_add_f32_e32 v92, v88, v89
	v_add_f32_e32 v93, v90, v91
	s_add_i32 s24, s24, s30
	v_add_f32_dpp v108, v108, v108 row_ror:8 row_mask:0xf bank_mask:0xf bound_ctrl:1
	v_add_f32_dpp v92, v92, v92 quad_perm:[1,0,3,2] row_mask:0xf bank_mask:0xf bound_ctrl:1
	v_add_f32_dpp v93, v93, v93 quad_perm:[1,0,3,2] row_mask:0xf bank_mask:0xf bound_ctrl:1
	buffer_store_dword v108, v110, s[44:47], s24 offen
	v_add_f32_dpp v92, v92, v92 quad_perm:[2,3,0,1] row_mask:0xf bank_mask:0xf bound_ctrl:1
	v_add_f32_dpp v93, v93, v93 quad_perm:[2,3,0,1] row_mask:0xf bank_mask:0xf bound_ctrl:1
	s_add_i32 s8, s8, s25
	v_add_f32_dpp v92, v92, v92 row_ror:4 row_mask:0xf bank_mask:0xf bound_ctrl:1
	v_add_f32_dpp v93, v93, v93 row_ror:4 row_mask:0xf bank_mask:0xf bound_ctrl:1
	v_add_f32_e32 v106, v102, v103
	v_add_f32_e32 v107, v104, v105
	buffer_load_dwordx2 v[64:65], v111, s[36:39], s8 offen
	s_waitcnt vmcnt(24)
	v_pk_mul_f32 v[94:95], v[66:67], v[36:37] op_sel_hi:[0,1]
	v_pk_mul_f32 v[98:99], v[66:67], v[36:37] op_sel:[1,0]
	v_pk_mul_f32 v[96:97], v[66:67], v[38:39] op_sel_hi:[0,1]
	v_pk_mul_f32 v[100:101], v[66:67], v[38:39] op_sel:[1,0]
	v_pk_fma_f32 v[94:95], v[80:81], v[28:29], v[94:95]
	v_pk_fma_f32 v[98:99], v[84:85], v[28:29], v[98:99]
	v_cndmask_b32_e64 v108, v106, v107, s[100:101]
	v_cndmask_b32_e64 v109, v107, v106, s[100:101]
	v_add_f32_dpp v92, v92, v92 row_ror:8 row_mask:0xf bank_mask:0xf bound_ctrl:1
	v_add_f32_dpp v93, v93, v93 row_ror:8 row_mask:0xf bank_mask:0xf bound_ctrl:1
	v_pk_fma_f32 v[96:97], v[82:83], v[30:31], v[96:97]
	v_pk_fma_f32 v[100:101], v[86:87], v[30:31], v[100:101]
	v_pk_fma_f32 v[80:81], v[32:33], v[92:93], v[94:95] op_sel_hi:[1,0,1] neg_lo:[0,1,0] neg_hi:[0,1,0]
	v_pk_fma_f32 v[84:85], v[32:33], v[92:93], v[98:99] op_sel:[0,1,0] neg_lo:[0,1,0] neg_hi:[0,1,0]
	v_add_f32_dpp v108, v109, v108 quad_perm:[1,0,3,2] row_mask:0xf bank_mask:0xf bound_ctrl:1
	v_pk_fma_f32 v[82:83], v[34:35], v[92:93], v[96:97] op_sel_hi:[1,0,1] neg_lo:[0,1,0] neg_hi:[0,1,0]
	v_pk_fma_f32 v[86:87], v[34:35], v[92:93], v[100:101] op_sel:[0,1,0] neg_lo:[0,1,0] neg_hi:[0,1,0]
	v_pk_mul_f32 v[102:103], v[80:81], v[24:25]
	v_pk_mul_f32 v[104:105], v[84:85], v[24:25]
	v_pk_fma_f32 v[102:103], v[82:83], v[26:27], v[102:103]
	v_pk_fma_f32 v[104:105], v[86:87], v[26:27], v[104:105]
	v_add_f32_dpp v108, v108, v108 quad_perm:[2,3,0,1] row_mask:0xf bank_mask:0xf bound_ctrl:1
	ds_read_b128 v[20:23], v112 offset:11008
	ds_read_b128 v[24:27], v112 offset:12032
	v_add_f32_dpp v108, v108, v108 row_ror:4 row_mask:0xf bank_mask:0xf bound_ctrl:1
	ds_read_b128 v[28:31], v112 offset:13056
	ds_read_b128 v[32:35], v112 offset:14080
	ds_read_b128 v[36:39], v112 offset:15104
	s_add_i32 s24, s24, s30
	v_add_f32_dpp v108, v108, v108 row_ror:8 row_mask:0xf bank_mask:0xf bound_ctrl:1
	s_waitcnt lgkmcnt(5)
	v_pk_mul_f32 v[88:89], v[80:81], v[0:1]
	v_pk_mul_f32 v[90:91], v[84:85], v[0:1]
	buffer_store_dword v108, v110, s[44:47], s24 offen
	v_add_f32_e32 v106, v102, v103
	v_add_f32_e32 v107, v104, v105
	v_pk_fma_f32 v[88:89], v[82:83], v[2:3], v[88:89]
	v_pk_fma_f32 v[90:91], v[86:87], v[2:3], v[90:91]
	v_cndmask_b32_e64 v108, v106, v107, s[100:101]
	v_cndmask_b32_e64 v109, v107, v106, s[100:101]
	v_add_f32_e32 v92, v88, v89
	v_add_f32_e32 v93, v90, v91
	v_add_f32_dpp v108, v109, v108 quad_perm:[1,0,3,2] row_mask:0xf bank_mask:0xf bound_ctrl:1
	v_add_f32_dpp v92, v92, v92 quad_perm:[1,0,3,2] row_mask:0xf bank_mask:0xf bound_ctrl:1
	v_add_f32_dpp v93, v93, v93 quad_perm:[1,0,3,2] row_mask:0xf bank_mask:0xf bound_ctrl:1
	v_add_f32_dpp v108, v108, v108 quad_perm:[2,3,0,1] row_mask:0xf bank_mask:0xf bound_ctrl:1
	v_add_f32_dpp v92, v92, v92 quad_perm:[2,3,0,1] row_mask:0xf bank_mask:0xf bound_ctrl:1
	v_add_f32_dpp v93, v93, v93 quad_perm:[2,3,0,1] row_mask:0xf bank_mask:0xf bound_ctrl:1
	s_add_i32 s8, s8, s25
	v_add_f32_dpp v108, v108, v108 row_ror:4 row_mask:0xf bank_mask:0xf bound_ctrl:1
	v_add_f32_dpp v92, v92, v92 row_ror:4 row_mask:0xf bank_mask:0xf bound_ctrl:1
	v_add_f32_dpp v93, v93, v93 row_ror:4 row_mask:0xf bank_mask:0xf bound_ctrl:1
	s_add_i32 s24, s24, s30
	v_add_f32_dpp v108, v108, v108 row_ror:8 row_mask:0xf bank_mask:0xf bound_ctrl:1
	buffer_load_dwordx2 v[66:67], v111, s[36:39], s8 offen
	s_waitcnt vmcnt(24)
	v_pk_mul_f32 v[94:95], v[68:69], v[16:17] op_sel_hi:[0,1]
	v_pk_mul_f32 v[98:99], v[68:69], v[16:17] op_sel:[1,0]
	v_pk_mul_f32 v[96:97], v[68:69], v[18:19] op_sel_hi:[0,1]
	v_pk_mul_f32 v[100:101], v[68:69], v[18:19] op_sel:[1,0]
	v_pk_fma_f32 v[94:95], v[80:81], v[8:9], v[94:95]
	v_pk_fma_f32 v[98:99], v[84:85], v[8:9], v[98:99]
	v_add_f32_dpp v92, v92, v92 row_ror:8 row_mask:0xf bank_mask:0xf bound_ctrl:1
	v_add_f32_dpp v93, v93, v93 row_ror:8 row_mask:0xf bank_mask:0xf bound_ctrl:1
	v_pk_fma_f32 v[96:97], v[82:83], v[10:11], v[96:97]
	v_pk_fma_f32 v[100:101], v[86:87], v[10:11], v[100:101]
	v_pk_fma_f32 v[80:81], v[12:13], v[92:93], v[94:95] op_sel_hi:[1,0,1] neg_lo:[0,1,0] neg_hi:[0,1,0]
	v_pk_fma_f32 v[84:85], v[12:13], v[92:93], v[98:99] op_sel:[0,1,0] neg_lo:[0,1,0] neg_hi:[0,1,0]
	buffer_store_dword v108, v110, s[44:47], s24 offen
	v_pk_fma_f32 v[82:83], v[14:15], v[92:93], v[96:97] op_sel_hi:[1,0,1] neg_lo:[0,1,0] neg_hi:[0,1,0]
	v_pk_fma_f32 v[86:87], v[14:15], v[92:93], v[100:101] op_sel:[0,1,0] neg_lo:[0,1,0] neg_hi:[0,1,0]
	v_pk_mul_f32 v[102:103], v[80:81], v[4:5]
	v_pk_mul_f32 v[104:105], v[84:85], v[4:5]
	v_pk_fma_f32 v[102:103], v[82:83], v[6:7], v[102:103]
	v_pk_fma_f32 v[104:105], v[86:87], v[6:7], v[104:105]
	s_add_i32 s8, s8, s25
	buffer_load_dwordx2 v[68:69], v111, s[36:39], s8 offen
	s_waitcnt vmcnt(31)
	ds_read_b128 v[0:3], v112 offset:15360
	ds_read_b128 v[4:7], v112 offset:16384
	ds_read_b128 v[8:11], v112 offset:17408
	ds_read_b128 v[12:15], v112 offset:18432
	ds_read_b128 v[16:19], v112 offset:19456
	s_waitcnt lgkmcnt(5)
	v_pk_mul_f32 v[88:89], v[80:81], v[20:21]
	v_pk_mul_f32 v[90:91], v[84:85], v[20:21]
	v_pk_fma_f32 v[88:89], v[82:83], v[22:23], v[88:89]
	v_pk_fma_f32 v[90:91], v[86:87], v[22:23], v[90:91]
	v_add_f32_e32 v92, v88, v89
	v_add_f32_e32 v93, v90, v91
	s_waitcnt vmcnt(24)
	v_add_f32_dpp v92, v92, v92 quad_perm:[1,0,3,2] row_mask:0xf bank_mask:0xf bound_ctrl:1
	v_add_f32_dpp v93, v93, v93 quad_perm:[1,0,3,2] row_mask:0xf bank_mask:0xf bound_ctrl:1
	v_pk_mul_f32 v[94:95], v[70:71], v[36:37] op_sel_hi:[0,1]
	v_add_f32_dpp v92, v92, v92 quad_perm:[2,3,0,1] row_mask:0xf bank_mask:0xf bound_ctrl:1
	v_add_f32_dpp v93, v93, v93 quad_perm:[2,3,0,1] row_mask:0xf bank_mask:0xf bound_ctrl:1
	v_pk_mul_f32 v[98:99], v[70:71], v[36:37] op_sel:[1,0]
	v_add_f32_dpp v92, v92, v92 row_ror:4 row_mask:0xf bank_mask:0xf bound_ctrl:1
	v_add_f32_dpp v93, v93, v93 row_ror:4 row_mask:0xf bank_mask:0xf bound_ctrl:1
	v_add_f32_e32 v106, v102, v103
	v_add_f32_e32 v107, v104, v105
	v_cndmask_b32_e64 v108, v106, v107, s[100:101]
	v_cndmask_b32_e64 v109, v107, v106, s[100:101]
	v_pk_mul_f32 v[96:97], v[70:71], v[38:39] op_sel_hi:[0,1]
	v_pk_mul_f32 v[100:101], v[70:71], v[38:39] op_sel:[1,0]
	v_pk_fma_f32 v[94:95], v[80:81], v[28:29], v[94:95]
	v_pk_fma_f32 v[98:99], v[84:85], v[28:29], v[98:99]
	v_add_f32_dpp v92, v92, v92 row_ror:8 row_mask:0xf bank_mask:0xf bound_ctrl:1
	v_add_f32_dpp v93, v93, v93 row_ror:8 row_mask:0xf bank_mask:0xf bound_ctrl:1
	v_pk_fma_f32 v[96:97], v[82:83], v[30:31], v[96:97]
	v_pk_fma_f32 v[100:101], v[86:87], v[30:31], v[100:101]
	v_pk_fma_f32 v[80:81], v[32:33], v[92:93], v[94:95] op_sel_hi:[1,0,1] neg_lo:[0,1,0] neg_hi:[0,1,0]
	v_pk_fma_f32 v[84:85], v[32:33], v[92:93], v[98:99] op_sel:[0,1,0] neg_lo:[0,1,0] neg_hi:[0,1,0]
	v_add_f32_dpp v108, v109, v108 quad_perm:[1,0,3,2] row_mask:0xf bank_mask:0xf bound_ctrl:1
	v_pk_fma_f32 v[82:83], v[34:35], v[92:93], v[96:97] op_sel_hi:[1,0,1] neg_lo:[0,1,0] neg_hi:[0,1,0]
	v_pk_fma_f32 v[86:87], v[34:35], v[92:93], v[100:101] op_sel:[0,1,0] neg_lo:[0,1,0] neg_hi:[0,1,0]
	v_pk_mul_f32 v[102:103], v[80:81], v[24:25]
	v_pk_mul_f32 v[104:105], v[84:85], v[24:25]
	v_add_f32_dpp v108, v108, v108 quad_perm:[2,3,0,1] row_mask:0xf bank_mask:0xf bound_ctrl:1
	v_pk_fma_f32 v[102:103], v[82:83], v[26:27], v[102:103]
	v_pk_fma_f32 v[104:105], v[86:87], v[26:27], v[104:105]
	ds_read_b128 v[20:23], v112 offset:15616
	v_add_f32_dpp v108, v108, v108 row_ror:4 row_mask:0xf bank_mask:0xf bound_ctrl:1
	ds_read_b128 v[24:27], v112 offset:16640
	s_add_i32 s9, s9, s17
	ds_read_b128 v[28:31], v112 offset:17664
	ds_read_b128 v[32:35], v112 offset:18688
	s_add_i32 s16, s16, s18
	s_add_i32 s24, s24, s30
	v_add_f32_dpp v108, v108, v108 row_ror:8 row_mask:0xf bank_mask:0xf bound_ctrl:1
	ds_read_b128 v[36:39], v112 offset:19712
	s_waitcnt lgkmcnt(5)
	v_pk_mul_f32 v[88:89], v[80:81], v[0:1]
	v_pk_mul_f32 v[90:91], v[84:85], v[0:1]
	buffer_store_dword v108, v110, s[44:47], s24 offen
	v_pk_fma_f32 v[88:89], v[82:83], v[2:3], v[88:89]
	v_pk_fma_f32 v[90:91], v[86:87], v[2:3], v[90:91]
	s_add_u32 m0, s19, 0x2800
	s_nop 0
	v_add_f32_e32 v92, v88, v89
	v_add_f32_e32 v93, v90, v91
	s_add_i32 s8, s8, s25
	v_add_f32_dpp v92, v92, v92 quad_perm:[1,0,3,2] row_mask:0xf bank_mask:0xf bound_ctrl:1
	v_add_f32_dpp v93, v93, v93 quad_perm:[1,0,3,2] row_mask:0xf bank_mask:0xf bound_ctrl:1
	buffer_load_dwordx2 v[70:71], v111, s[36:39], s8 offen
	buffer_load_dwordx4 v113, s[36:39], s9 offen lds
	buffer_load_dwordx4 v114, s[36:39], s9 offen offset:1024 lds
	buffer_load_dwordx4 v115, s[40:43], s16 offen offset:2048 lds
	buffer_load_dwordx4 v116, s[40:43], s16 offen offset:3072 lds
	s_add_u32 m0, s19, 0x3800
	s_nop 0
	v_add_f32_dpp v92, v92, v92 quad_perm:[2,3,0,1] row_mask:0xf bank_mask:0xf bound_ctrl:1
	v_add_f32_dpp v93, v93, v93 quad_perm:[2,3,0,1] row_mask:0xf bank_mask:0xf bound_ctrl:1
	buffer_load_dwordx4 v117, s[40:43], s16 offen lds
	s_waitcnt vmcnt(24)
	v_add_f32_dpp v92, v92, v92 row_ror:4 row_mask:0xf bank_mask:0xf bound_ctrl:1
	v_add_f32_dpp v93, v93, v93 row_ror:4 row_mask:0xf bank_mask:0xf bound_ctrl:1
	v_pk_mul_f32 v[94:95], v[72:73], v[16:17] op_sel_hi:[0,1]
	v_pk_mul_f32 v[98:99], v[72:73], v[16:17] op_sel:[1,0]
	v_pk_mul_f32 v[96:97], v[72:73], v[18:19] op_sel_hi:[0,1]
	v_pk_mul_f32 v[100:101], v[72:73], v[18:19] op_sel:[1,0]
	v_pk_fma_f32 v[94:95], v[80:81], v[8:9], v[94:95]
	v_pk_fma_f32 v[98:99], v[84:85], v[8:9], v[98:99]
	v_add_f32_e32 v106, v102, v103
	v_add_f32_e32 v107, v104, v105
	v_add_f32_dpp v92, v92, v92 row_ror:8 row_mask:0xf bank_mask:0xf bound_ctrl:1
	v_add_f32_dpp v93, v93, v93 row_ror:8 row_mask:0xf bank_mask:0xf bound_ctrl:1
	v_pk_fma_f32 v[96:97], v[82:83], v[10:11], v[96:97]
	v_pk_fma_f32 v[100:101], v[86:87], v[10:11], v[100:101]
	v_pk_fma_f32 v[80:81], v[12:13], v[92:93], v[94:95] op_sel_hi:[1,0,1] neg_lo:[0,1,0] neg_hi:[0,1,0]
	v_pk_fma_f32 v[84:85], v[12:13], v[92:93], v[98:99] op_sel:[0,1,0] neg_lo:[0,1,0] neg_hi:[0,1,0]
	v_pk_fma_f32 v[82:83], v[14:15], v[92:93], v[96:97] op_sel_hi:[1,0,1] neg_lo:[0,1,0] neg_hi:[0,1,0]
	v_pk_fma_f32 v[86:87], v[14:15], v[92:93], v[100:101] op_sel:[0,1,0] neg_lo:[0,1,0] neg_hi:[0,1,0]
	v_pk_mul_f32 v[102:103], v[80:81], v[4:5]
	v_pk_mul_f32 v[104:105], v[84:85], v[4:5]
	v_pk_fma_f32 v[102:103], v[82:83], v[6:7], v[102:103]
	v_pk_fma_f32 v[104:105], v[86:87], v[6:7], v[104:105]
	v_cndmask_b32_e64 v108, v106, v107, s[100:101]
	v_cndmask_b32_e64 v109, v107, v106, s[100:101]
	ds_read_b128 v[0:3], v112 offset:15872
	ds_read_b128 v[4:7], v112 offset:16896
	v_add_f32_dpp v108, v109, v108 quad_perm:[1,0,3,2] row_mask:0xf bank_mask:0xf bound_ctrl:1
	ds_read_b128 v[8:11], v112 offset:17920
	ds_read_b128 v[12:15], v112 offset:18944
	ds_read_b128 v[16:19], v112 offset:19968
	v_add_f32_dpp v108, v108, v108 quad_perm:[2,3,0,1] row_mask:0xf bank_mask:0xf bound_ctrl:1
	s_waitcnt lgkmcnt(5)
	v_pk_mul_f32 v[88:89], v[80:81], v[20:21]
	v_pk_mul_f32 v[90:91], v[84:85], v[20:21]
	v_add_f32_dpp v108, v108, v108 row_ror:4 row_mask:0xf bank_mask:0xf bound_ctrl:1
	v_pk_fma_f32 v[88:89], v[82:83], v[22:23], v[88:89]
	v_pk_fma_f32 v[90:91], v[86:87], v[22:23], v[90:91]
	v_add_f32_e32 v92, v88, v89
	v_add_f32_e32 v93, v90, v91
	s_add_i32 s24, s24, s30
	v_add_f32_dpp v108, v108, v108 row_ror:8 row_mask:0xf bank_mask:0xf bound_ctrl:1
	v_add_f32_dpp v92, v92, v92 quad_perm:[1,0,3,2] row_mask:0xf bank_mask:0xf bound_ctrl:1
	v_add_f32_dpp v93, v93, v93 quad_perm:[1,0,3,2] row_mask:0xf bank_mask:0xf bound_ctrl:1
	buffer_store_dword v108, v110, s[44:47], s24 offen
	v_add_f32_dpp v92, v92, v92 quad_perm:[2,3,0,1] row_mask:0xf bank_mask:0xf bound_ctrl:1
	v_add_f32_dpp v93, v93, v93 quad_perm:[2,3,0,1] row_mask:0xf bank_mask:0xf bound_ctrl:1
	s_add_i32 s8, s8, s25
	v_add_f32_dpp v92, v92, v92 row_ror:4 row_mask:0xf bank_mask:0xf bound_ctrl:1
	v_add_f32_dpp v93, v93, v93 row_ror:4 row_mask:0xf bank_mask:0xf bound_ctrl:1
	v_add_f32_e32 v106, v102, v103
	v_add_f32_e32 v107, v104, v105
	buffer_load_dwordx2 v[72:73], v111, s[36:39], s8 offen
	s_waitcnt vmcnt(24)
	v_pk_mul_f32 v[94:95], v[74:75], v[36:37] op_sel_hi:[0,1]
	v_pk_mul_f32 v[98:99], v[74:75], v[36:37] op_sel:[1,0]
	v_pk_mul_f32 v[96:97], v[74:75], v[38:39] op_sel_hi:[0,1]
	v_pk_mul_f32 v[100:101], v[74:75], v[38:39] op_sel:[1,0]
	v_pk_fma_f32 v[94:95], v[80:81], v[28:29], v[94:95]
	v_pk_fma_f32 v[98:99], v[84:85], v[28:29], v[98:99]
	v_cndmask_b32_e64 v108, v106, v107, s[100:101]
	v_cndmask_b32_e64 v109, v107, v106, s[100:101]
	v_add_f32_dpp v92, v92, v92 row_ror:8 row_mask:0xf bank_mask:0xf bound_ctrl:1
	v_add_f32_dpp v93, v93, v93 row_ror:8 row_mask:0xf bank_mask:0xf bound_ctrl:1
	v_pk_fma_f32 v[96:97], v[82:83], v[30:31], v[96:97]
	v_pk_fma_f32 v[100:101], v[86:87], v[30:31], v[100:101]
	v_pk_fma_f32 v[80:81], v[32:33], v[92:93], v[94:95] op_sel_hi:[1,0,1] neg_lo:[0,1,0] neg_hi:[0,1,0]
	v_pk_fma_f32 v[84:85], v[32:33], v[92:93], v[98:99] op_sel:[0,1,0] neg_lo:[0,1,0] neg_hi:[0,1,0]
	v_add_f32_dpp v108, v109, v108 quad_perm:[1,0,3,2] row_mask:0xf bank_mask:0xf bound_ctrl:1
	v_pk_fma_f32 v[82:83], v[34:35], v[92:93], v[96:97] op_sel_hi:[1,0,1] neg_lo:[0,1,0] neg_hi:[0,1,0]
	v_pk_fma_f32 v[86:87], v[34:35], v[92:93], v[100:101] op_sel:[0,1,0] neg_lo:[0,1,0] neg_hi:[0,1,0]
	v_pk_mul_f32 v[102:103], v[80:81], v[24:25]
	v_pk_mul_f32 v[104:105], v[84:85], v[24:25]
	v_pk_fma_f32 v[102:103], v[82:83], v[26:27], v[102:103]
	v_pk_fma_f32 v[104:105], v[86:87], v[26:27], v[104:105]
	v_add_f32_dpp v108, v108, v108 quad_perm:[2,3,0,1] row_mask:0xf bank_mask:0xf bound_ctrl:1
	ds_read_b128 v[20:23], v112 offset:16128
	ds_read_b128 v[24:27], v112 offset:17152
	v_add_f32_dpp v108, v108, v108 row_ror:4 row_mask:0xf bank_mask:0xf bound_ctrl:1
	ds_read_b128 v[28:31], v112 offset:18176
	ds_read_b128 v[32:35], v112 offset:19200
	ds_read_b128 v[36:39], v112 offset:20224
	s_add_i32 s24, s24, s30
	v_add_f32_dpp v108, v108, v108 row_ror:8 row_mask:0xf bank_mask:0xf bound_ctrl:1
	s_waitcnt lgkmcnt(5)
	v_pk_mul_f32 v[88:89], v[80:81], v[0:1]
	v_pk_mul_f32 v[90:91], v[84:85], v[0:1]
	buffer_store_dword v108, v110, s[44:47], s24 offen
	v_add_f32_e32 v106, v102, v103
	v_add_f32_e32 v107, v104, v105
	v_pk_fma_f32 v[88:89], v[82:83], v[2:3], v[88:89]
	v_pk_fma_f32 v[90:91], v[86:87], v[2:3], v[90:91]
	v_cndmask_b32_e64 v108, v106, v107, s[100:101]
	v_cndmask_b32_e64 v109, v107, v106, s[100:101]
	v_add_f32_e32 v92, v88, v89
	v_add_f32_e32 v93, v90, v91
	v_add_f32_dpp v108, v109, v108 quad_perm:[1,0,3,2] row_mask:0xf bank_mask:0xf bound_ctrl:1
	v_add_f32_dpp v92, v92, v92 quad_perm:[1,0,3,2] row_mask:0xf bank_mask:0xf bound_ctrl:1
	v_add_f32_dpp v93, v93, v93 quad_perm:[1,0,3,2] row_mask:0xf bank_mask:0xf bound_ctrl:1
	v_add_f32_dpp v108, v108, v108 quad_perm:[2,3,0,1] row_mask:0xf bank_mask:0xf bound_ctrl:1
	v_add_f32_dpp v92, v92, v92 quad_perm:[2,3,0,1] row_mask:0xf bank_mask:0xf bound_ctrl:1
	v_add_f32_dpp v93, v93, v93 quad_perm:[2,3,0,1] row_mask:0xf bank_mask:0xf bound_ctrl:1
	s_add_i32 s8, s8, s25
	v_add_f32_dpp v108, v108, v108 row_ror:4 row_mask:0xf bank_mask:0xf bound_ctrl:1
	v_add_f32_dpp v92, v92, v92 row_ror:4 row_mask:0xf bank_mask:0xf bound_ctrl:1
	v_add_f32_dpp v93, v93, v93 row_ror:4 row_mask:0xf bank_mask:0xf bound_ctrl:1
	s_add_i32 s24, s24, s30
	v_add_f32_dpp v108, v108, v108 row_ror:8 row_mask:0xf bank_mask:0xf bound_ctrl:1
	buffer_load_dwordx2 v[74:75], v111, s[36:39], s8 offen
	s_waitcnt vmcnt(24)
	v_pk_mul_f32 v[94:95], v[76:77], v[16:17] op_sel_hi:[0,1]
	v_pk_mul_f32 v[98:99], v[76:77], v[16:17] op_sel:[1,0]
	v_pk_mul_f32 v[96:97], v[76:77], v[18:19] op_sel_hi:[0,1]
	v_pk_mul_f32 v[100:101], v[76:77], v[18:19] op_sel:[1,0]
	v_pk_fma_f32 v[94:95], v[80:81], v[8:9], v[94:95]
	v_pk_fma_f32 v[98:99], v[84:85], v[8:9], v[98:99]
	v_add_f32_dpp v92, v92, v92 row_ror:8 row_mask:0xf bank_mask:0xf bound_ctrl:1
	v_add_f32_dpp v93, v93, v93 row_ror:8 row_mask:0xf bank_mask:0xf bound_ctrl:1
	v_pk_fma_f32 v[96:97], v[82:83], v[10:11], v[96:97]
	v_pk_fma_f32 v[100:101], v[86:87], v[10:11], v[100:101]
	v_pk_fma_f32 v[80:81], v[12:13], v[92:93], v[94:95] op_sel_hi:[1,0,1] neg_lo:[0,1,0] neg_hi:[0,1,0]
	v_pk_fma_f32 v[84:85], v[12:13], v[92:93], v[98:99] op_sel:[0,1,0] neg_lo:[0,1,0] neg_hi:[0,1,0]
	buffer_store_dword v108, v110, s[44:47], s24 offen
	v_pk_fma_f32 v[82:83], v[14:15], v[92:93], v[96:97] op_sel_hi:[1,0,1] neg_lo:[0,1,0] neg_hi:[0,1,0]
	v_pk_fma_f32 v[86:87], v[14:15], v[92:93], v[100:101] op_sel:[0,1,0] neg_lo:[0,1,0] neg_hi:[0,1,0]
	v_pk_mul_f32 v[102:103], v[80:81], v[4:5]
	v_pk_mul_f32 v[104:105], v[84:85], v[4:5]
	v_pk_fma_f32 v[102:103], v[82:83], v[6:7], v[102:103]
	v_pk_fma_f32 v[104:105], v[86:87], v[6:7], v[104:105]
	s_add_i32 s8, s8, s25
	buffer_load_dwordx2 v[76:77], v111, s[36:39], s8 offen
	s_waitcnt vmcnt(32)
	ds_read_b128 v[0:3], v112 offset:0
	ds_read_b128 v[4:7], v112 offset:1024
	ds_read_b128 v[8:11], v112 offset:2048
	ds_read_b128 v[12:15], v112 offset:3072
	ds_read_b128 v[16:19], v112 offset:4096
	s_waitcnt lgkmcnt(5)
	v_pk_mul_f32 v[88:89], v[80:81], v[20:21]
	v_pk_mul_f32 v[90:91], v[84:85], v[20:21]
	v_pk_fma_f32 v[88:89], v[82:83], v[22:23], v[88:89]
	v_pk_fma_f32 v[90:91], v[86:87], v[22:23], v[90:91]
	v_add_f32_e32 v92, v88, v89
	v_add_f32_e32 v93, v90, v91
	v_add_f32_e32 v106, v102, v103
	v_add_f32_e32 v107, v104, v105
	v_add_f32_dpp v92, v92, v92 quad_perm:[1,0,3,2] row_mask:0xf bank_mask:0xf bound_ctrl:1
	v_add_f32_dpp v93, v93, v93 quad_perm:[1,0,3,2] row_mask:0xf bank_mask:0xf bound_ctrl:1
	v_cndmask_b32_e64 v108, v106, v107, s[100:101]
	v_cndmask_b32_e64 v109, v107, v106, s[100:101]
	v_add_f32_dpp v92, v92, v92 quad_perm:[2,3,0,1] row_mask:0xf bank_mask:0xf bound_ctrl:1
	v_add_f32_dpp v93, v93, v93 quad_perm:[2,3,0,1] row_mask:0xf bank_mask:0xf bound_ctrl:1
	v_add_f32_dpp v108, v109, v108 quad_perm:[1,0,3,2] row_mask:0xf bank_mask:0xf bound_ctrl:1
	s_waitcnt vmcnt(24)
	v_add_f32_dpp v92, v92, v92 row_ror:4 row_mask:0xf bank_mask:0xf bound_ctrl:1
	v_add_f32_dpp v93, v93, v93 row_ror:4 row_mask:0xf bank_mask:0xf bound_ctrl:1
	v_pk_mul_f32 v[94:95], v[78:79], v[36:37] op_sel_hi:[0,1]
	v_pk_mul_f32 v[98:99], v[78:79], v[36:37] op_sel:[1,0]
	v_add_f32_dpp v108, v108, v108 quad_perm:[2,3,0,1] row_mask:0xf bank_mask:0xf bound_ctrl:1
	v_pk_mul_f32 v[96:97], v[78:79], v[38:39] op_sel_hi:[0,1]
	v_pk_mul_f32 v[100:101], v[78:79], v[38:39] op_sel:[1,0]
	v_pk_fma_f32 v[94:95], v[80:81], v[28:29], v[94:95]
	v_pk_fma_f32 v[98:99], v[84:85], v[28:29], v[98:99]
	v_add_f32_dpp v92, v92, v92 row_ror:8 row_mask:0xf bank_mask:0xf bound_ctrl:1
	v_add_f32_dpp v93, v93, v93 row_ror:8 row_mask:0xf bank_mask:0xf bound_ctrl:1
	v_add_f32_dpp v108, v108, v108 row_ror:4 row_mask:0xf bank_mask:0xf bound_ctrl:1
	v_pk_fma_f32 v[96:97], v[82:83], v[30:31], v[96:97]
	v_pk_fma_f32 v[100:101], v[86:87], v[30:31], v[100:101]
	v_pk_fma_f32 v[80:81], v[32:33], v[92:93], v[94:95] op_sel_hi:[1,0,1] neg_lo:[0,1,0] neg_hi:[0,1,0]
	v_pk_fma_f32 v[84:85], v[32:33], v[92:93], v[98:99] op_sel:[0,1,0] neg_lo:[0,1,0] neg_hi:[0,1,0]
	v_pk_fma_f32 v[82:83], v[34:35], v[92:93], v[96:97] op_sel_hi:[1,0,1] neg_lo:[0,1,0] neg_hi:[0,1,0]
	v_pk_fma_f32 v[86:87], v[34:35], v[92:93], v[100:101] op_sel:[0,1,0] neg_lo:[0,1,0] neg_hi:[0,1,0]
	v_pk_mul_f32 v[102:103], v[80:81], v[24:25]
	v_pk_mul_f32 v[104:105], v[84:85], v[24:25]
	s_add_i32 s24, s24, s30
	v_add_f32_dpp v108, v108, v108 row_ror:8 row_mask:0xf bank_mask:0xf bound_ctrl:1
	v_pk_fma_f32 v[102:103], v[82:83], v[26:27], v[102:103]
	v_pk_fma_f32 v[104:105], v[86:87], v[26:27], v[104:105]
	buffer_store_dword v108, v110, s[44:47], s24 offen
	v_add_f32_e32 v106, v102, v103
	v_add_f32_e32 v107, v104, v105
	v_cndmask_b32_e64 v108, v106, v107, s[100:101]
	v_cndmask_b32_e64 v109, v107, v106, s[100:101]
	s_add_i32 s9, s9, s17
	s_add_i32 s16, s16, s18
	v_add_f32_dpp v108, v109, v108 quad_perm:[1,0,3,2] row_mask:0xf bank_mask:0xf bound_ctrl:1
	s_add_i32 s24, s24, s30
	s_add_i32 s8, s8, s25
	v_add_f32_dpp v108, v108, v108 quad_perm:[2,3,0,1] row_mask:0xf bank_mask:0xf bound_ctrl:1
	buffer_load_dwordx2 v[78:79], v111, s[36:39], s8 offen
	s_add_i32 s8, s8, s25
	v_add_f32_dpp v108, v108, v108 row_ror:4 row_mask:0xf bank_mask:0xf bound_ctrl:1
	s_nop 0
	s_nop 0
	v_add_f32_dpp v108, v108, v108 row_ror:8 row_mask:0xf bank_mask:0xf bound_ctrl:1
	s_add_i32 s98, s98, -1
	s_cmp_lg_u32 s98, 0
	s_cbranch_scc1 .Lss_loop
	s_nop 1
	buffer_store_dword v108, v110, s[44:47], s24 offen
	s_waitcnt vmcnt(0) lgkmcnt(0)
	s_lshl_b32 s3, s94, 1
	s_add_i32 s2, s2, s3
	s_branch .Lss_item
